# P0 tile loop: all eight next-tile DMA addresses computed before the barrier; DMAs issue back to back after it
# baseline (speedup 1.0000x reference)
.LBB0_103:
	s_bitcmp1_b32 s65, 0
	s_cselect_b32 s73, 0, 0x10400
	s_add_i32 s89, s73, 0
	s_add_i32 s73, s88, s11
	s_mul_i32 s74, s71, s73
	s_mul_hi_u32 s75, s70, s73
	s_add_i32 s75, s75, s74
	s_mul_i32 s74, s70, s73
	s_lshl_b64 s[74:75], s[74:75], 2
	s_add_u32 s74, s0, s74
	s_addc_u32 s75, s1, s75
	s_ashr_i32 s73, s72, 31
	s_lshl_b64 s[72:73], s[72:73], 2
	s_add_u32 s74, s74, s72
	s_addc_u32 s75, s75, s73
	v_lshl_add_u64 v[32:33], s[74:75], 0, v[0:1]
	s_add_i32 s74, s88, s33
	s_mul_i32 s75, s71, s74
	s_mul_hi_u32 s90, s70, s74
	s_add_i32 s75, s90, s75
	s_mul_i32 s74, s70, s74
	s_add_i32 s98, s89, s3
	s_lshl_b64 s[74:75], s[74:75], 2
	s_add_u32 s74, s0, s74
	s_addc_u32 s75, s1, s75
	s_add_u32 s74, s74, s72
	s_addc_u32 s75, s75, s73
	v_lshl_add_u64 v[34:35], s[74:75], 0, v[0:1]
	s_add_i32 s74, s88, s35
	s_mul_i32 s75, s71, s74
	s_mul_hi_u32 s90, s70, s74
	s_add_i32 s75, s90, s75
	s_mul_i32 s74, s70, s74
	s_add_i32 s89, s89, s34
	s_lshl_b64 s[74:75], s[74:75], 2
	s_add_u32 s74, s0, s74
	s_addc_u32 s75, s1, s75
	s_add_u32 s74, s74, s72
	s_addc_u32 s75, s75, s73
	v_lshl_add_u64 v[36:37], s[74:75], 0, v[0:1]
	s_add_i32 s74, s88, s56
	s_mul_i32 s75, s71, s74
	s_mul_hi_u32 s90, s70, s74
	s_add_i32 s75, s90, s75
	s_mul_i32 s74, s70, s74
	s_lshl_b64 s[74:75], s[74:75], 2
	s_add_u32 s74, s0, s74
	s_addc_u32 s75, s1, s75
	s_add_u32 s74, s74, s72
	s_addc_u32 s75, s75, s73
	v_lshl_add_u64 v[38:39], s[74:75], 0, v[0:1]
	s_add_i32 s74, s88, s57
	s_mul_i32 s75, s71, s74
	s_mul_hi_u32 s90, s70, s74
	s_add_i32 s75, s90, s75
	s_mul_i32 s74, s70, s74
	s_lshl_b64 s[74:75], s[74:75], 2
	s_add_u32 s74, s0, s74
	s_addc_u32 s75, s1, s75
	s_add_u32 s74, s74, s72
	s_addc_u32 s75, s75, s73
	v_lshl_add_u64 v[40:41], s[74:75], 0, v[0:1]
	s_add_i32 s74, s88, s59
	s_mul_i32 s75, s71, s74
	s_mul_hi_u32 s90, s70, s74
	s_add_i32 s75, s90, s75
	s_mul_i32 s74, s70, s74
	s_lshl_b64 s[74:75], s[74:75], 2
	s_add_u32 s74, s0, s74
	s_addc_u32 s75, s1, s75
	s_add_u32 s74, s74, s72
	s_addc_u32 s75, s75, s73
	v_lshl_add_u64 v[42:43], s[74:75], 0, v[0:1]
	s_add_i32 s74, s88, s61
	s_mul_i32 s75, s71, s74
	s_mul_hi_u32 s90, s70, s74
	s_add_i32 s75, s90, s75
	s_mul_i32 s74, s70, s74
	s_lshl_b64 s[74:75], s[74:75], 2
	s_add_u32 s74, s0, s74
	s_addc_u32 s75, s1, s75
	s_add_u32 s74, s74, s72
	s_addc_u32 s75, s75, s73
	v_lshl_add_u64 v[44:45], s[74:75], 0, v[0:1]
	s_add_i32 s74, s88, s64
	s_mul_i32 s71, s71, s74
	s_mul_hi_u32 s75, s70, s74
	s_add_i32 s71, s75, s71
	s_mul_i32 s70, s70, s74
	s_lshl_b64 s[70:71], s[70:71], 2
	s_add_u32 s0, s0, s70
	s_addc_u32 s1, s1, s71
	s_add_u32 s0, s0, s72
	s_addc_u32 s1, s1, s73
	v_lshl_add_u64 v[46:47], s[0:1], 0, v[0:1]
.Lp0_desc_done:
	s_waitcnt vmcnt(0) lgkmcnt(0)
	s_barrier
	s_cmp_lg_u32 s101, 0
	s_cbranch_scc1 .LBB0_104
	s_mov_b32 m0, s98
	s_nop 0
	global_load_lds_dwordx4 v[32:33], off nt
	s_mov_b32 m0, s89
	s_nop 0
	global_load_lds_dwordx4 v[34:35], off nt
	s_add_i32 m0, s89, 0x410
	s_nop 0
	global_load_lds_dwordx4 v[36:37], off nt
	s_add_i32 m0, s89, 0x820
	s_nop 0
	global_load_lds_dwordx4 v[38:39], off nt
	s_add_i32 m0, s89, 0xc30
	s_nop 0
	global_load_lds_dwordx4 v[40:41], off nt
	s_add_i32 m0, s89, 0x1040
	s_nop 0
	global_load_lds_dwordx4 v[42:43], off nt
	s_add_i32 m0, s89, 0x1450
	s_nop 0
	global_load_lds_dwordx4 v[44:45], off nt
	s_add_i32 m0, s89, 0x1860
	s_nop 0
	global_load_lds_dwordx4 v[46:47], off nt
